# combo7 (SG epilogue+K-loop load batching, pop prefetch, P0 GEMV pipelining) + last 40 weight-conversion chunks moved from the QKV phase to idle 5-unit CUs at the end of FFN1
# speedup vs baseline: 1.0024x; 1.0024x over previous
; #define LAS __attribute__((address_space(3)))
; __device__ __forceinline__ unsigned xb_add(unsigned* p, unsigned v) { return __hip_atomic_fetch_add(p, v, __ATOMIC_RELAXED, __HIP_MEMORY_SCOPE_AGENT); }
; __device__ __forceinline__ unsigned xb_xcc_id() { return (unsigned)__builtin_amdgcn_s_getreg((3 << 11) | 20) & 0xFu; }
; __device__ __forceinline__ XcdBarrier xcd_barrier_post(unsigned* bar, volatile LAS unsigned* st) {
;     XcdBarrier b; b.bar = bar; b.x = xb_xcc_id(); b.st = st;
;     if (threadIdx.x == 0) (void)xb_add(&bar[XB_XCNT(b.x)], 1u);
;     return b;
; }
; __global__ void __launch_bounds__(NTHREADS, 2) mega_fwd(Params P) {
;     extern __shared__ __attribute__((aligned(16))) unsigned char lds[];
;     cg::grid_group grid = cg::this_grid();
;     LAS unsigned char* ldsl = (LAS unsigned char*)lds;
;     const int G = gridDim.x, bx = blockIdx.x;
;     ...
;     { volatile LAS unsigned* st0 = (volatile LAS unsigned*)(ldsl + RING_BYTES + 2048); if (threadIdx.x < 2) st0[threadIdx.x] = 0u; __syncthreads(); }
;     const unsigned xbar_x = xcd_barrier_post(ctl + 4096, (volatile LAS unsigned*)(ldsl + RING_BYTES + 2048)).x;
_Z8mega_fwd6Params:
	s_mov_b32 s101, 0
	s_load_dwordx8 s[72:79], s[0:1], 0xa0
	s_load_dwordx8 s[4:11], s[0:1], 0x80
	s_load_dword s36, s[0:1], 0xc0
	s_mov_b32 s70, s2
	s_add_u32 s2, s0, 0xb8
	v_and_b32_e32 v214, 0x3ff, v0
	s_waitcnt lgkmcnt(0)
	v_writelane_b32 v253, s4, 0
	s_addc_u32 s3, s1, 0
	v_cmp_gt_u32_e32 vcc, 2, v214
	v_writelane_b32 v253, s5, 1
	v_writelane_b32 v253, s6, 2
	v_writelane_b32 v253, s7, 3
	v_writelane_b32 v253, s8, 4
	v_writelane_b32 v253, s9, 5
	v_writelane_b32 v253, s10, 6
	v_writelane_b32 v253, s11, 7
	s_and_saveexec_b64 s[4:5], vcc
	v_lshl_add_u32 v1, v214, 2, 0
	v_add_u32_e32 v1, 0x20800, v1
	v_mov_b32_e32 v2, 0
	ds_write_b32 v1, v2
	s_or_b64 exec, exec, s[4:5]
	s_mov_b64 s[6:7], s[76:77]
	s_waitcnt lgkmcnt(0)
	s_barrier
	s_getreg_b32 s4, hwreg(HW_REG_XCC_ID, 0, 4)
	s_and_b32 s4, s4, 15
	v_writelane_b32 v253, s4, 8
	v_cmp_eq_u32_e64 s[62:63], 0, v214
	s_and_saveexec_b64 s[4:5], s[62:63]
	s_cbranch_execz .LBB0_4
	v_readlane_b32 s8, v253, 8
	s_lshl_b32 s8, s8, 8
	s_add_u32 s6, s6, s8
	s_addc_u32 s7, s7, 0
	v_mov_b32_e32 v1, s6
	v_add_co_u32_e32 v2, vcc, 0x4000, v1
	v_mov_b32_e32 v1, s7
	s_nop 0
	v_addc_co_u32_e32 v3, vcc, 0, v1, vcc
	v_mov_b32_e32 v1, 1
	flat_atomic_add v[2:3], v1 offset:1024

; #define LAS __attribute__((address_space(3)))
; __device__ __forceinline__ int opaque_tid() { int t; asm volatile("v_mov_b32 %0, %1" : "=v"(t) : "v"((int)threadIdx.x)); return t; }
; #define ws (opq(P.ws))
; __device__ __forceinline__ void conv_item(const Params& P, int l, int r, LAS float* scr, int lane) {
;     unsigned char* wsb = P.ws;
;     bf16_t* Win_ = (bf16_t*)(wsb + WS_WIN); bf16_t* Wo_ = (bf16_t*)(wsb + WS_WO); bf16_t* Wf1_ = (bf16_t*)(wsb + WS_WF1); bf16_t* Wf2_ = (bf16_t*)(wsb + WS_WF2);
;     if (r < CV_IN) { const int kb = r / 72, gd = r % 72; transpose_item(P.w_in + (size_t)l * DM * DIN, DIN, win_srccol(gd), nullptr, Win_ + (size_t)l * DIN * DM, DM, 32 * gd, 64 * kb, scr, lane); return; } r -= CV_IN;
;     if (r < CV_O) { const int kb = r / 32, gd = r % 32; transpose_item(P.w_o + (size_t)l * DM * DM, DM, 32 * gd, P.g_out + l * DM, Wo_ + (size_t)l * DM * DM, DM, 32 * gd, 64 * kb, scr, lane); return; } r -= CV_O;
;     if (r < CV_F1) { const int kb = r / 176, gd = r % 176; const int pn = gd >> 3, j = gd & 7, bj = j >> 2, wc = j & 3;
;         transpose_item(P.w_ffn_in + (size_t)l * DM * 2 * DFF, 2 * DFF, bj * DFF + 128 * pn + 32 * wc, nullptr, Wf1_ + (size_t)l * 2 * DFF * DM, DM, 32 * gd, 64 * kb, scr, lane); return; } r -= CV_F1;
;     { const int kb = r / 32, gd = r % 32; transpose_item(P.w_ffn_out + (size_t)l * DFF * DM, DM, 32 * gd, nullptr, Wf2_ + (size_t)l * DM * DFF, DFF, 32 * gd, 64 * kb, scr, lane); }
; __global__ void __launch_bounds__(NTHREADS, 2) mega_fwd(Params P) {
;     ...
;         if (!lastl && bx >= 82) {
;             const int t_ = opaque_tid(), w_ = __builtin_amdgcn_readfirstlane(t_ >> 6);
;             for (int c = bx - 82; c < CV_L / 8; c += G - 82) conv_item(P, l + 1, c * 8 + w_, (LAS float*)(ldsl + w_ * 8448), t_ & 63);
.Lconv_entry:
	s_ashr_i32 s6, s0, 6
	v_readlane_b32 s0, v252, 9
	s_add_i32 s7, s0, 1
	s_mul_i32 s0, s6, 0x2100
	v_readlane_b32 s12, v253, 0
	s_add_i32 s4, s0, 0
	s_mul_i32 s8, s7, 0xb00000
	v_readlane_b32 s16, v253, 4
	v_readlane_b32 s1, v252, 10
	s_mul_hi_u32 s5, s7, 0xb00000
	v_readlane_b32 s17, v253, 5
	s_add_u32 s0, s16, s8
	s_addc_u32 s1, s17, s5
	s_mul_i32 s2, s7, 0x580000
	v_readlane_b32 s10, v253, 41
	v_lshlrev_b32_e32 v0, 4, v2
	s_mul_hi_u32 s3, s7, 0x580000
	v_readlane_b32 s11, v253, 42
	s_add_u32 s2, s10, s2
	v_bfe_u32 v17, v2, 3, 3
	v_and_b32_e32 v0, 0x70, v0
	v_lshlrev_b32_e32 v2, 3, v2
	v_readlane_b32 s14, v253, 2
	s_addc_u32 s3, s11, s3
	v_lshl_add_u64 v[14:15], s[0:1], 0, v[0:1]
	v_and_b32_e32 v2, 56, v2
	s_mul_i32 s0, s7, 0x1600000
	v_readlane_b32 s15, v253, 3
	v_mul_u32_u24_e32 v4, 0x84, v2
	v_lshlrev_b32_e32 v2, 1, v2
	v_mov_b32_e32 v3, v1
	s_mul_hi_u32 s1, s7, 0x1600000
	s_add_u32 s0, s14, s0
	s_waitcnt vmcnt(0)
	v_lshl_add_u64 v[42:43], s[2:3], 0, v[2:3]
	s_addc_u32 s1, s15, s1
	v_readlane_b32 s2, v253, 43
	v_readlane_b32 s3, v253, 44
	s_add_u32 s2, s2, s8
	s_addc_u32 s3, s3, s5
	s_lshl_b32 s86, s7, 20
	v_lshl_add_u64 v[44:45], s[0:1], 0, v[0:1]
	s_lshl_b64 s[0:1], s[86:87], 2
	v_lshl_add_u64 v[46:47], s[2:3], 0, v[2:3]
	s_add_u32 s2, s28, s0
	s_addc_u32 s3, s29, s1
	s_lshl_b32 s86, s7, 10
	s_lshl_b64 s[0:1], s[86:87], 2
	v_lshlrev_b32_e32 v5, 2, v17
	s_add_u32 s0, s26, s0
	v_add_u32_e32 v62, s4, v0
	v_add3_u32 v67, s4, v4, v5
	s_addc_u32 s1, s27, s1
	s_lshl_b32 s4, s7, 21
	v_readlane_b32 s8, v253, 47
	v_readlane_b32 s13, v253, 1
	v_readlane_b32 s18, v253, 6
	v_readlane_b32 s19, v253, 7
	v_readlane_b32 s9, v253, 48
	s_add_u32 s4, s8, s4
	s_addc_u32 s5, s9, 0
	v_readlane_b32 s8, v253, 9
	v_readlane_b32 s16, v253, 17
	v_readlane_b32 s17, v253, 18
	v_readlane_b32 s18, v253, 19
	v_readlane_b32 s19, v253, 20
	v_readlane_b32 s20, v253, 21
	v_readlane_b32 s21, v253, 22
	v_lshl_add_u64 v[48:49], s[2:3], 0, v[0:1]
	s_mul_i32 s2, s7, 0x900000
	v_readlane_b32 s22, v253, 23
	v_readlane_b32 s23, v253, 24
	s_mov_b64 s[16:17], s[20:21]
	s_mul_hi_u32 s3, s7, 0x900000
	v_readlane_b32 s9, v253, 10
	s_add_u32 s2, s16, s2
	v_lshl_add_u64 v[50:51], s[4:5], 0, v[2:3]
	s_addc_u32 s3, s17, s3
	s_mul_hi_u32 s5, s7, 0x480000
	s_mul_i32 s7, s7, 0x480000
	v_readlane_b32 s8, v253, 49
	v_or_b32_e32 v4, 32, v17
	v_readlane_b32 s12, v253, 13
	v_readlane_b32 s13, v253, 14
	v_readlane_b32 s9, v253, 50
	s_add_u32 s4, s8, s7
	v_lshl_add_u64 v[52:53], s[2:3], 0, v[0:1]
	v_readlane_b32 s2, v254, 31
	v_mul_u32_u24_e32 v4, 0x84, v4
	v_readlane_b32 s14, v253, 15
	v_readlane_b32 s15, v253, 16
	s_mov_b64 s[18:19], s[22:23]
	s_addc_u32 s5, s9, s5
	s_add_i32 s2, s2, s6
	s_cmp_eq_u32 s101, 2
	s_cbranch_scc0 .Lxc1
	s_add_i32 s2, s100, s6
.Lxc1:
	v_readlane_b32 s12, v253, 45
	v_mul_u32_u24_e32 v63, 0x84, v17
	v_or_b32_e32 v64, 8, v17
	v_or_b32_e32 v65, 16, v17
	v_or_b32_e32 v66, 24, v17
	v_lshl_add_u64 v[54:55], s[4:5], 0, v[2:3]
	s_lshl_b32 s3, s2, 5
	s_lshl_b32 s8, s2, 1
	v_add_u32_e32 v68, v62, v4
	v_readlane_b32 s9, v254, 4
	v_readlane_b32 s13, v253, 46
	v_readlane_b32 s14, v254, 7
	v_readlane_b32 s15, v254, 32
	v_readlane_b32 s16, v254, 33
	v_readlane_b32 s17, v254, 35
	s_movk_i32 s18, 0x7fff
	s_mov_b32 s19, 0xffff0000
	s_movk_i32 s20, 0x2400
	v_readlane_b32 s10, v253, 11
	v_readlane_b32 s11, v253, 12
	s_cmp_eq_u32 s101, 2
	s_cbranch_scc0 .Lxc2
	s_lshr_b32 s9, s100, 3
.Lxc2:
	s_branch .LBB0_350
; #define LAS __attribute__((address_space(3)))
; __device__ __forceinline__ unsigned pk2(float lo, float hi) { return f2bf(lo) | (f2bf(hi) << 16); }
; __device__ __forceinline__ void transpose_item(const float* W, int N, int srccol, const float* kscale, bf16_t* WT, int K, int dstrow, int k0, LAS float* scr, int lane) {
;     f32x4 t[8];
; #pragma unroll
;     for (int i = 0; i < 8; ++i) t[i] = __builtin_nontemporal_load((const f32x4*)(W + (size_t)(k0 + 8 * i + (lane >> 3)) * N + srccol + 4 * (lane & 7)));
; #pragma unroll
;     for (int i = 0; i < 8; ++i) { const int kk = 8 * i + (lane >> 3); f32x4 v = t[i]; if (kscale) v = v * kscale[k0 + kk];
;         LAS float* d = scr + kk * 33 + 4 * (lane & 7); d[0] = v[0]; d[1] = v[1]; d[2] = v[2]; d[3] = v[3]; }
;     asm volatile("s_waitcnt lgkmcnt(0)" ::: "memory");
;     const int c = lane & 7;
; #pragma unroll
;     for (int j = 0; j < 4; ++j) { const int n = (lane >> 3) + 8 * j; const LAS float* s = scr + (8 * c) * 33 + n;
;         u32x4 o; o.x = pk2(s[0 * 33], s[1 * 33]); o.y = pk2(s[2 * 33], s[3 * 33]); o.z = pk2(s[4 * 33], s[5 * 33]); o.w = pk2(s[6 * 33], s[7 * 33]);
;         *(u32x4*)(WT + (size_t)(dstrow + n) * K + k0 + 8 * c) = o; }
;     asm volatile("s_waitcnt lgkmcnt(0)" ::: "memory");
; }
.LBB0_348:
	s_lshl_b32 s4, s7, 6
	s_ashr_i32 s7, s6, 31
	v_or_b32_e32 v0, s4, v17
	v_lshl_add_u64 v[34:35], s[6:7], 2, v[52:53]
	v_mad_i64_i32 v[2:3], s[6:7], v0, s20, v[34:35]
	v_or_b32_e32 v6, 8, v0
	global_load_dwordx4 v[2:5], v[2:3], off nt
	v_mad_i64_i32 v[6:7], s[6:7], v6, s20, v[34:35]
	global_load_dwordx4 v[6:9], v[6:7], off nt
	v_or_b32_e32 v10, 16, v0
	v_mad_i64_i32 v[10:11], s[6:7], v10, s20, v[34:35]
	global_load_dwordx4 v[10:13], v[10:11], off nt
	v_or_b32_e32 v18, 24, v0
	v_mad_i64_i32 v[18:19], s[6:7], v18, s20, v[34:35]
	global_load_dwordx4 v[18:21], v[18:19], off nt
	v_or_b32_e32 v22, 32, v0
	v_mad_i64_i32 v[22:23], s[6:7], v22, s20, v[34:35]
	global_load_dwordx4 v[22:25], v[22:23], off nt
	v_or_b32_e32 v26, 40, v0
	v_mad_i64_i32 v[26:27], s[6:7], v26, s20, v[34:35]
	global_load_dwordx4 v[26:29], v[26:27], off nt
	v_or_b32_e32 v30, 48, v0
	v_mad_i64_i32 v[30:31], s[6:7], v30, s20, v[34:35]
	global_load_dwordx4 v[30:33], v[30:31], off nt
	v_or_b32_e32 v0, 56, v0
	v_mad_i64_i32 v[34:35], s[6:7], v0, s20, v[34:35]
	global_load_dwordx4 v[34:37], v[34:35], off nt
	v_add_u32_e32 v0, v62, v63
	s_ashr_i32 s5, s4, 31
	s_waitcnt vmcnt(0)
	ds_write2_b32 v0, v2, v3 offset1:1
	ds_write2_b32 v0, v4, v5 offset0:2 offset1:3
	v_add_u32_e32 v2, 0x420, v0
	ds_write2_b32 v2, v6, v7 offset1:1
	v_add_u32_e32 v2, 0x428, v0
	ds_write2_b32 v2, v8, v9 offset1:1
	v_add_u32_e32 v2, 0x840, v0
	ds_write2_b32 v2, v10, v11 offset1:1
	v_add_u32_e32 v2, 0x848, v0
	ds_write2_b32 v2, v12, v13 offset1:1
	v_add_u32_e32 v2, 0xc60, v0
	ds_write2_b32 v2, v18, v19 offset1:1
	v_add_u32_e32 v2, 0xc68, v0
	ds_write2_b32 v2, v20, v21 offset1:1
	v_add_u32_e32 v2, 0x1080, v0
	ds_write2_b32 v2, v22, v23 offset1:1
	v_add_u32_e32 v2, 0x1088, v0
	ds_write2_b32 v2, v24, v25 offset1:1
	v_add_u32_e32 v2, 0x14a0, v0
	ds_write2_b32 v2, v26, v27 offset1:1
	v_add_u32_e32 v2, 0x14a8, v0
	ds_write2_b32 v2, v28, v29 offset1:1
	v_add_u32_e32 v2, 0x18c0, v0
	ds_write2_b32 v2, v30, v31 offset1:1
	v_add_u32_e32 v2, 0x18c8, v0
	ds_write2_b32 v2, v32, v33 offset1:1
	v_add_u32_e32 v2, 0x1ce0, v0
	v_add_u32_e32 v0, 0x1ce8, v0
	ds_write2_b32 v2, v34, v35 offset1:1
	ds_write2_b32 v0, v36, v37 offset1:1
	s_waitcnt lgkmcnt(0)
	ds_read2_b32 v[8:9], v67 offset0:33 offset1:41
	ds_read2_b32 v[10:11], v67 offset1:8
	ds_read2_b32 v[12:13], v67 offset0:66 offset1:74
	ds_read2_b32 v[18:19], v67 offset0:99 offset1:107
	ds_read2_b32 v[20:21], v67 offset0:132 offset1:140
	ds_read2_b32 v[22:23], v67 offset0:165 offset1:173
	ds_read2_b32 v[24:25], v67 offset0:198 offset1:206
	ds_read2_b32 v[26:27], v67 offset0:231 offset1:239
	s_waitcnt lgkmcnt(0)
	v_bfe_u32 v4, v8, 16, 1
	v_bfe_u32 v0, v10, 16, 1
	v_add3_u32 v0, v10, v0, s18
	v_lshrrev_b32_e32 v0, 16, v0
	v_add3_u32 v4, v8, v4, s18
	v_and_or_b32 v4, v4, s19, v0
	v_bfe_u32 v0, v12, 16, 1
	v_add3_u32 v0, v12, v0, s18
	v_bfe_u32 v5, v18, 16, 1
	v_lshrrev_b32_e32 v0, 16, v0
	v_add3_u32 v5, v18, v5, s18
	v_and_or_b32 v5, v5, s19, v0
	v_bfe_u32 v0, v20, 16, 1
	v_add3_u32 v0, v20, v0, s18
	v_bfe_u32 v6, v22, 16, 1
	v_lshrrev_b32_e32 v0, 16, v0
	v_add3_u32 v6, v22, v6, s18
	v_and_or_b32 v6, v6, s19, v0
	v_bfe_u32 v0, v24, 16, 1
	v_or_b32_e32 v28, s10, v17
	v_add3_u32 v0, v24, v0, s18
	v_bfe_u32 v7, v26, 16, 1
	v_ashrrev_i32_e32 v29, 31, v28
	v_lshl_add_u64 v[2:3], s[4:5], 1, v[54:55]
	v_lshrrev_b32_e32 v0, 16, v0
	v_add3_u32 v7, v26, v7, s18
	v_lshlrev_b64 v[28:29], 11, v[28:29]
	v_and_or_b32 v7, v7, s19, v0
	v_lshl_add_u64 v[28:29], v[2:3], 0, v[28:29]
	v_bfe_u32 v0, v11, 16, 1
	global_store_dwordx4 v[28:29], v[4:7], off
	v_add3_u32 v0, v11, v0, s18
	v_lshrrev_b32_e32 v0, 16, v0
	v_bfe_u32 v4, v9, 16, 1
	v_add3_u32 v4, v9, v4, s18
	v_and_or_b32 v4, v4, s19, v0
	v_bfe_u32 v0, v13, 16, 1
	v_add3_u32 v0, v13, v0, s18
	v_bfe_u32 v5, v19, 16, 1
	v_lshrrev_b32_e32 v0, 16, v0
	v_add3_u32 v5, v19, v5, s18
	v_and_or_b32 v5, v5, s19, v0
	v_bfe_u32 v0, v21, 16, 1
	v_add3_u32 v0, v21, v0, s18
	v_bfe_u32 v6, v23, 16, 1
	v_lshrrev_b32_e32 v0, 16, v0
	v_add3_u32 v6, v23, v6, s18
	v_and_or_b32 v6, v6, s19, v0
	v_bfe_u32 v0, v25, 16, 1
	v_or_b32_e32 v8, s10, v64
	v_add3_u32 v0, v25, v0, s18
	v_bfe_u32 v7, v27, 16, 1
	v_ashrrev_i32_e32 v9, 31, v8
	v_lshrrev_b32_e32 v0, 16, v0
	v_add3_u32 v7, v27, v7, s18
	v_lshlrev_b64 v[8:9], 11, v[8:9]
	v_and_or_b32 v7, v7, s19, v0
	v_lshl_add_u64 v[8:9], v[2:3], 0, v[8:9]
	global_store_dwordx4 v[8:9], v[4:7], off
	ds_read2_b32 v[8:9], v67 offset0:49 offset1:57
	ds_read2_b32 v[10:11], v67 offset0:16 offset1:24
	ds_read2_b32 v[12:13], v67 offset0:82 offset1:90
	ds_read2_b32 v[18:19], v67 offset0:115 offset1:123
	ds_read2_b32 v[20:21], v67 offset0:148 offset1:156
	ds_read2_b32 v[22:23], v67 offset0:181 offset1:189
	ds_read2_b32 v[24:25], v67 offset0:214 offset1:222
	ds_read2_b32 v[26:27], v67 offset0:247 offset1:255
	s_waitcnt lgkmcnt(7)
	v_bfe_u32 v4, v8, 16, 1
	s_waitcnt lgkmcnt(6)
	v_bfe_u32 v0, v10, 16, 1
	v_add3_u32 v0, v10, v0, s18
	v_lshrrev_b32_e32 v0, 16, v0
	v_add3_u32 v4, v8, v4, s18
	v_and_or_b32 v4, v4, s19, v0
	s_waitcnt lgkmcnt(5)
	v_bfe_u32 v0, v12, 16, 1
	v_add3_u32 v0, v12, v0, s18
	s_waitcnt lgkmcnt(4)
	v_bfe_u32 v5, v18, 16, 1
	v_lshrrev_b32_e32 v0, 16, v0
	v_add3_u32 v5, v18, v5, s18
	v_and_or_b32 v5, v5, s19, v0
	s_waitcnt lgkmcnt(3)
	v_bfe_u32 v0, v20, 16, 1
	v_add3_u32 v0, v20, v0, s18
	s_waitcnt lgkmcnt(2)
	v_bfe_u32 v6, v22, 16, 1
	v_lshrrev_b32_e32 v0, 16, v0
	v_add3_u32 v6, v22, v6, s18
	v_and_or_b32 v6, v6, s19, v0
	s_waitcnt lgkmcnt(1)
	v_bfe_u32 v0, v24, 16, 1
	v_or_b32_e32 v28, s10, v65
	v_add3_u32 v0, v24, v0, s18
	s_waitcnt lgkmcnt(0)
	v_bfe_u32 v7, v26, 16, 1
	v_ashrrev_i32_e32 v29, 31, v28
	v_lshrrev_b32_e32 v0, 16, v0
	v_add3_u32 v7, v26, v7, s18
	v_lshlrev_b64 v[28:29], 11, v[28:29]
	v_and_or_b32 v7, v7, s19, v0
	v_lshl_add_u64 v[28:29], v[2:3], 0, v[28:29]
	v_bfe_u32 v0, v11, 16, 1
	global_store_dwordx4 v[28:29], v[4:7], off
	v_add3_u32 v0, v11, v0, s18
	v_lshrrev_b32_e32 v0, 16, v0
	v_bfe_u32 v4, v9, 16, 1
	v_add3_u32 v4, v9, v4, s18
	v_and_or_b32 v4, v4, s19, v0
	v_bfe_u32 v0, v13, 16, 1
	v_add3_u32 v0, v13, v0, s18
	v_bfe_u32 v5, v19, 16, 1
	v_lshrrev_b32_e32 v0, 16, v0
	v_add3_u32 v5, v19, v5, s18
	v_and_or_b32 v5, v5, s19, v0
	v_bfe_u32 v0, v21, 16, 1
	v_add3_u32 v0, v21, v0, s18
	v_bfe_u32 v6, v23, 16, 1
	v_lshrrev_b32_e32 v0, 16, v0
	v_add3_u32 v6, v23, v6, s18
	v_and_or_b32 v6, v6, s19, v0
	v_bfe_u32 v0, v25, 16, 1
	v_or_b32_e32 v8, s10, v66
	v_add3_u32 v0, v25, v0, s18
	v_bfe_u32 v7, v27, 16, 1
	v_ashrrev_i32_e32 v9, 31, v8
	v_lshrrev_b32_e32 v0, 16, v0
	v_add3_u32 v7, v27, v7, s18
	v_lshlrev_b64 v[8:9], 11, v[8:9]
	v_and_or_b32 v7, v7, s19, v0
	v_lshl_add_u64 v[2:3], v[2:3], 0, v[8:9]
	global_store_dwordx4 v[2:3], v[4:7], off
	s_waitcnt lgkmcnt(0)
.LBB0_349:
	s_add_i32 s9, s9, s14
	s_add_i32 s2, s2, s15
	s_add_i32 s3, s3, s16
	s_add_i32 s8, s8, s17
	s_cmpk_lt_i32 s9, 0x2b8
	s_cbranch_scc0 .LBB0_393

; __device__ __forceinline__ unsigned xb_add(unsigned* p, unsigned v) { return __hip_atomic_fetch_add(p, v, __ATOMIC_RELAXED, __HIP_MEMORY_SCOPE_AGENT); }
; __device__ __forceinline__ void xcd_barrier(const XcdBarrier& b) {
;     asm volatile("s_waitcnt vmcnt(0)" ::: "memory");
;     __syncthreads();
;     if (threadIdx.x == 0) {
;         unsigned* bar = b.bar;
;         __builtin_amdgcn_s_waitcnt(0);
;         unsigned nloc = b.st[0], nx = b.st[1];
;         if (nloc == 0u) { xcd_barrier_complete(bar, b.x, nloc, nx); b.st[0] = nloc; b.st[1] = nx; }
;         const unsigned old = xb_add(&bar[XB_XSUB(b.x)], 1u);
.LBB0_393:
	s_cmp_eq_u32 s101, 2
	s_cbranch_scc1 .Lxconv_ret
	s_mov_b64 s[36:37], s[76:77]
	s_waitcnt vmcnt(0)
	s_waitcnt vmcnt(0) lgkmcnt(0)
	s_barrier
	s_and_saveexec_b64 s[34:35], s[62:63]
	v_writelane_b32 v252, s60, 13
	s_nop 1
	v_writelane_b32 v252, s61, 14
	s_cbranch_execz .LBB0_437
	v_readlane_b32 s0, v254, 40
	s_waitcnt vmcnt(0) expcnt(0) lgkmcnt(0)
	s_nop 0
	v_mov_b32_e32 v0, s0
	ds_read_b32 v2, v0
	v_readlane_b32 s0, v254, 41
	s_waitcnt lgkmcnt(0)
	v_cmp_ne_u32_e32 vcc, 0, v2
	v_mov_b32_e32 v0, s0
	ds_read_b32 v0, v0
	s_cbranch_vccnz .LBB0_408
	s_add_u32 s0, s36, 0x4200
	s_addc_u32 s1, s37, 0
	s_add_u32 s4, s36, 0x4400
	s_addc_u32 s5, s37, 0
	s_add_u32 s6, s36, 0x4500
	s_addc_u32 s7, s37, 0
	s_add_u32 s8, s36, 0x4600
	s_addc_u32 s9, s37, 0
	s_add_u32 s10, s36, 0x4700
	s_addc_u32 s11, s37, 0
	s_add_u32 s12, s36, 0x4800
	s_addc_u32 s13, s37, 0
	s_add_u32 s14, s36, 0x4900
	s_addc_u32 s15, s37, 0
	s_add_u32 s16, s36, 0x4a00
	s_addc_u32 s17, s37, 0
	s_add_u32 s18, s36, 0x4b00
	s_addc_u32 s19, s37, 0
	s_add_u32 s20, s36, 0x4c00
	s_addc_u32 s21, s37, 0
	s_add_u32 s22, s36, 0x4d00
	s_addc_u32 s23, s37, 0
	s_add_u32 s24, s36, 0x4e00
	s_addc_u32 s25, s37, 0
	s_add_u32 s26, s36, 0x4f00
	s_addc_u32 s27, s37, 0
	s_add_u32 s28, s36, 0x5000
	s_addc_u32 s29, s37, 0
	s_add_u32 s30, s36, 0x5100
	s_addc_u32 s31, s37, 0
	s_add_u32 s38, s36, 0x5200
	s_addc_u32 s39, s37, 0
	s_add_u32 s40, s36, 0x5300
	s_addc_u32 s41, s37, 0
	s_mov_b32 s2, 1
	s_mov_b64 s[42:43], 0
	s_branch .LBB0_398

; #define LAS __attribute__((address_space(3)))
; __device__ __forceinline__ int opaque_tid() { int t; asm volatile("v_mov_b32 %0, %1" : "=v"(t) : "v"((int)threadIdx.x)); return t; }
; __global__ void __launch_bounds__(NTHREADS, 2) mega_fwd(Params P) {
;     ...
;         if (!lastl && bx >= 82) {
;             const int t_ = opaque_tid(), w_ = __builtin_amdgcn_readfirstlane(t_ >> 6);
;             for (int c = bx - 82; c < CV_L / 8; c += G - 82) conv_item(P, l + 1, c * 8 + w_, (LAS float*)(ldsl + w_ * 8448), t_ & 63);
;     ...
;         if (PH & 32) { pg8::Gemm g{Hb, Wf1 + (size_t)l * 2 * DFF * DM, MROWS, 2 * DFF, DM}; pg8::StaticOrder S; S.init(lastl ? 64 : 66, 2 * DFF, G, bx, lastl ? 1 : 0, 16);
;           pg8::EpiSwiGLU E{hid};
;           pg8::gemm_phase<pg8::EpiSwiGLU, pg8::StaticOrder, true, true>(ldsl, g, S, E); }
.LBB0_1114:
	v_readlane_b32 s100, v254, 57
	s_nop 3
	s_sub_i32 s100, s100, 0xac
	s_cmp_lt_u32 s100, 40
	s_cbranch_scc0 .Lxconv_skip
	v_readlane_b32 s14, v252, 9
	s_nop 3
	s_cmp_lg_u32 s14, 3
	s_cbranch_scc0 .Lxconv_skip
	s_addk_i32 s100, 0x2b8
	s_lshl_b32 s100, s100, 3
	s_mov_b32 s101, 2
	s_waitcnt vmcnt(0) lgkmcnt(0)
	s_barrier
	v_readlane_b32 s16, v253, 25
	v_readlane_b32 s26, v253, 35
	v_readlane_b32 s27, v253, 36
	v_readlane_b32 s28, v253, 37
	v_readlane_b32 s29, v253, 38
	v_readlane_b32 s17, v253, 26
	v_readlane_b32 s18, v253, 27
	v_readlane_b32 s19, v253, 28
	v_readlane_b32 s20, v253, 29
	v_readlane_b32 s21, v253, 30
	v_readlane_b32 s22, v253, 31
	v_readlane_b32 s23, v253, 32
	v_readlane_b32 s24, v253, 33
	v_readlane_b32 s25, v253, 34
	v_readlane_b32 s30, v253, 39
	v_readlane_b32 s31, v253, 40
	v_readlane_b32 s15, v252, 10
	v_mov_b32 v2, v214
	s_nop 0
	v_readfirstlane_b32 s0, v2
	s_nop 3
	s_branch .Lconv_entry
.Lxconv_ret:
	s_mov_b32 s101, 0
